# plus: P3 epilogue issues both halves' gate loads together
# baseline (speedup 1.0000x reference)
; __device__ __forceinline__ u32x4 pack8(f32x4 a, f32x4 b) { u32x4 w; w.x = cvt_pk_bf16(a[0], a[1]); w.y = cvt_pk_bf16(a[2], a[3]); w.z = cvt_pk_bf16(b[0], b[1]); w.w = cvt_pk_bf16(b[2], b[3]); return w; }
;     __device__ __forceinline__ bool operator()(f32x4 (&acc)[2][2][4][2], const Unit& u, int wr, int wc, int fr, int fq) const {
;         const int row0 = u.pm * BM + wr * 64 + fr, col0 = u.pn * BM + wc * 32 + 8 * fq;
;         const bf16_t* G = (u.half == 0) ? GSA : GSB;
; #pragma unroll
;         for (int ai = 0; ai < 2; ++ai) {
;             u32x4 gv[4][2];
; #pragma unroll
;             for (int m = 0; m < 4; ++m)
; #pragma unroll
;                 for (int bj = 0; bj < 2; ++bj) gv[m][bj] = *(const u32x4*)(G + (size_t)(row0 + ai * HALF + m * 16) * DM + col0 + bj * HALF);
; #pragma unroll
;             for (int m = 0; m < 4; ++m)
; #pragma unroll
;                 for (int bj = 0; bj < 2; ++bj) {
;                     const u32x4 gw = gv[m][bj];
;                     const float fg[8] = {bflo(gw.x), bfhi(gw.x), bflo(gw.y), bfhi(gw.y), bflo(gw.z), bfhi(gw.z), bflo(gw.w), bfhi(gw.w)};
; #pragma unroll
;                     for (int n = 0; n < 2; ++n)
; #pragma unroll
;                         for (int i = 0; i < 4; ++i) acc[ai][bj][m][n][i] *= fg[4 * n + i];
;                     if (u.half != 0) *(u32x4*)(O + (size_t)(row0 + ai * HALF + m * 16) * DM + col0 + bj * HALF) = pack8(acc[ai][bj][m][0], acc[ai][bj][m][1]);
.LBB0_514:
	s_cmp_lg_u32 s5, 0
	v_lshl_add_u32 v176, s36, 8, v187
	s_cselect_b64 s[36:37], -1, 0
	s_cmp_eq_u32 s5, 0
	v_lshl_or_b32 v172, s4, 8, v189
	s_cselect_b64 s[4:5], -1, 0
	s_and_b64 vcc, s[4:5], exec
	s_cselect_b32 s4, s72, 0x1be00000
	s_add_u32 s4, s52, s4
	s_addc_u32 s5, s53, 0
	v_ashrrev_i32_e32 v173, 31, v172
	v_ashrrev_i32_e32 v177, 31, v176
	v_lshl_add_u64 v[174:175], v[172:173], 1, s[4:5]
	v_lshlrev_b64 v[184:185], 12, v[176:177]
	v_lshl_add_u64 v[128:129], v[174:175], 0, v[184:185]
	global_load_dwordx4 v[192:195], v[128:129], off
	global_load_dwordx4 v[152:155], v[128:129], off offset:256
	v_or_b32_e32 v128, 16, v176
	v_ashrrev_i32_e32 v129, 31, v128
	v_lshlrev_b64 v[182:183], 12, v[128:129]
	v_lshl_add_u64 v[128:129], v[174:175], 0, v[182:183]
	global_load_dwordx4 v[148:151], v[128:129], off
	global_load_dwordx4 v[144:147], v[128:129], off offset:256
	v_or_b32_e32 v128, 32, v176
	v_ashrrev_i32_e32 v129, 31, v128
	v_lshlrev_b64 v[180:181], 12, v[128:129]
	v_lshl_add_u64 v[128:129], v[174:175], 0, v[180:181]
	global_load_dwordx4 v[140:143], v[128:129], off
	global_load_dwordx4 v[136:139], v[128:129], off offset:256
	v_or_b32_e32 v128, 48, v176
	v_ashrrev_i32_e32 v129, 31, v128
	v_lshlrev_b64 v[178:179], 12, v[128:129]
	v_lshl_add_u64 v[128:129], v[174:175], 0, v[178:179]
	global_load_dwordx4 v[132:135], v[128:129], off
	s_nop 0
	global_load_dwordx4 v[128:131], v[128:129], off offset:256
	v_lshlrev_b64 v[232:233], 12, v[176:177]
	v_lshl_add_u64 v[234:235], v[174:175], 0, v[232:233]
	v_lshl_add_u64 v[236:237], v[234:235], 0, s[12:13]
	global_load_dwordx4 v[200:203], v[236:237], off
	global_load_dwordx4 v[204:207], v[236:237], off offset:256
	v_lshl_add_u64 v[236:237], v[234:235], 0, s[20:21]
	global_load_dwordx4 v[208:211], v[236:237], off
	global_load_dwordx4 v[212:215], v[236:237], off offset:256
	v_lshl_add_u64 v[236:237], v[234:235], 0, s[22:23]
	global_load_dwordx4 v[216:219], v[236:237], off
	global_load_dwordx4 v[220:223], v[236:237], off offset:256
	v_lshl_add_u64 v[236:237], v[234:235], 0, s[24:25]
	global_load_dwordx4 v[224:227], v[236:237], off
	global_load_dwordx4 v[228:231], v[236:237], off offset:256
	v_lshl_add_u64 v[184:185], s[8:9], 0, v[184:185]
	v_lshl_add_u64 v[184:185], v[172:173], 1, v[184:185]
	s_waitcnt vmcnt(8)
	v_lshlrev_b32_e32 v196, 16, v192
	v_and_b32_e32 v197, 0xffff0000, v192
	v_lshlrev_b32_e32 v192, 16, v193
	v_and_b32_e32 v193, 0xffff0000, v193
	v_lshlrev_b32_e32 v198, 16, v194
	v_and_b32_e32 v199, 0xffff0000, v194
	v_lshlrev_b32_e32 v194, 16, v195
	v_and_b32_e32 v195, 0xffff0000, v195
	v_pk_mul_f32 v[124:125], v[124:125], v[196:197]
	v_pk_mul_f32 v[126:127], v[126:127], v[192:193]
	v_pk_mul_f32 v[120:121], v[120:121], v[198:199]
	v_pk_mul_f32 v[122:123], v[122:123], v[194:195]
	s_cbranch_vccnz .LBB0_516
	v_cvt_pk_bf16_f32 v192, v124, v125
	v_cvt_pk_bf16_f32 v193, v126, v127
	v_cvt_pk_bf16_f32 v194, v120, v121
	v_cvt_pk_bf16_f32 v195, v122, v123
	global_store_dwordx4 v[184:185], v[192:195], off

; __device__ __forceinline__ u32x4 pack8(f32x4 a, f32x4 b) { u32x4 w; w.x = cvt_pk_bf16(a[0], a[1]); w.y = cvt_pk_bf16(a[2], a[3]); w.z = cvt_pk_bf16(b[0], b[1]); w.w = cvt_pk_bf16(b[2], b[3]); return w; }
;     __device__ __forceinline__ bool operator()(f32x4 (&acc)[2][2][4][2], const Unit& u, int wr, int wc, int fr, int fq) const {
;     ...
;         for (int ai = 0; ai < 2; ++ai) {
;             u32x4 gv[4][2];
; #pragma unroll
;             for (int m = 0; m < 4; ++m)
; #pragma unroll
;                 for (int bj = 0; bj < 2; ++bj) gv[m][bj] = *(const u32x4*)(G + (size_t)(row0 + ai * HALF + m * 16) * DM + col0 + bj * HALF);
; #pragma unroll
;             for (int m = 0; m < 4; ++m)
; #pragma unroll
;                 for (int bj = 0; bj < 2; ++bj) {
;                     const u32x4 gw = gv[m][bj];
;                     const float fg[8] = {bflo(gw.x), bfhi(gw.x), bflo(gw.y), bfhi(gw.y), bflo(gw.z), bfhi(gw.z), bflo(gw.w), bfhi(gw.w)};
; #pragma unroll
;                     for (int n = 0; n < 2; ++n)
; #pragma unroll
;                         for (int i = 0; i < 4; ++i) acc[ai][bj][m][n][i] *= fg[4 * n + i];
;                     if (u.half != 0) *(u32x4*)(O + (size_t)(row0 + ai * HALF + m * 16) * DM + col0 + bj * HALF) = pack8(acc[ai][bj][m][0], acc[ai][bj][m][1]);
;                 }
.LBB0_530:
	s_nop 1
	v_lshlrev_b64 v[128:129], 12, v[176:177]
	v_lshl_add_u64 v[192:193], v[128:129], 0, s[12:13]
	v_lshl_add_u64 v[180:181], v[128:129], 0, s[20:21]
	v_lshl_add_u64 v[178:179], v[128:129], 0, s[22:23]
	v_lshl_add_u64 v[130:131], v[174:175], 0, v[192:193]
	v_lshl_add_u64 v[176:177], v[128:129], 0, s[24:25]
	v_lshl_add_u64 v[128:129], v[174:175], 0, v[180:181]
	v_lshl_add_u64 v[132:133], v[174:175], 0, v[178:179]
	v_lshl_add_u64 v[174:175], v[174:175], 0, v[176:177]
	s_nop 0
	v_lshl_add_u64 v[174:175], s[8:9], 0, v[192:193]
	s_and_b64 vcc, exec, s[4:5]
	v_lshl_add_u64 v[174:175], v[172:173], 1, v[174:175]
	s_waitcnt vmcnt(7)
	v_lshlrev_b32_e32 v192, 16, v200
	v_and_b32_e32 v193, 0xffff0000, v200
	v_lshlrev_b32_e32 v182, 16, v201
	v_and_b32_e32 v183, 0xffff0000, v201
	v_lshlrev_b32_e32 v194, 16, v202
	v_and_b32_e32 v195, 0xffff0000, v202
	v_lshlrev_b32_e32 v184, 16, v203
	v_and_b32_e32 v185, 0xffff0000, v203
	v_pk_mul_f32 v[60:61], v[60:61], v[192:193]
	v_pk_mul_f32 v[62:63], v[62:63], v[182:183]
	v_pk_mul_f32 v[56:57], v[56:57], v[194:195]
	v_pk_mul_f32 v[58:59], v[58:59], v[184:185]
	s_cbranch_vccnz .LBB0_532
	v_cvt_pk_bf16_f32 v182, v60, v61
	v_cvt_pk_bf16_f32 v183, v62, v63
	v_cvt_pk_bf16_f32 v184, v56, v57
	v_cvt_pk_bf16_f32 v185, v58, v59
	global_store_dwordx4 v[174:175], v[182:185], off
.LBB0_532:
	s_waitcnt vmcnt(6)
	s_nop 0
	v_lshlrev_b32_e32 v182, 16, v204
	v_and_b32_e32 v183, 0xffff0000, v204
	v_lshlrev_b32_e32 v152, 16, v205
	v_and_b32_e32 v153, 0xffff0000, v205
	v_pk_mul_f32 v[30:31], v[30:31], v[152:153]
	v_lshlrev_b32_e32 v152, 16, v206
	v_and_b32_e32 v153, 0xffff0000, v206
	v_pk_mul_f32 v[24:25], v[24:25], v[152:153]
	v_lshlrev_b32_e32 v152, 16, v207
	v_and_b32_e32 v153, 0xffff0000, v207
	v_pk_mul_f32 v[28:29], v[28:29], v[182:183]
	s_and_b64 vcc, exec, s[4:5]
	v_pk_mul_f32 v[26:27], v[26:27], v[152:153]
	s_cbranch_vccnz .LBB0_534
	v_cvt_pk_bf16_f32 v152, v28, v29
	v_cvt_pk_bf16_f32 v153, v30, v31
	v_cvt_pk_bf16_f32 v154, v24, v25
	v_cvt_pk_bf16_f32 v155, v26, v27
	global_store_dwordx4 v[174:175], v[152:155], off offset:256
.LBB0_534:
	s_waitcnt vmcnt(5)
	s_nop 0
	v_lshlrev_b32_e32 v152, 16, v208
	v_and_b32_e32 v153, 0xffff0000, v208
	v_lshlrev_b32_e32 v148, 16, v209
	v_and_b32_e32 v149, 0xffff0000, v209
	v_pk_mul_f32 v[54:55], v[54:55], v[148:149]
	v_lshlrev_b32_e32 v148, 16, v210
	v_and_b32_e32 v149, 0xffff0000, v210
	v_pk_mul_f32 v[48:49], v[48:49], v[148:149]
	v_lshlrev_b32_e32 v148, 16, v211
	v_and_b32_e32 v149, 0xffff0000, v211
	v_pk_mul_f32 v[50:51], v[50:51], v[148:149]
	v_lshl_add_u64 v[148:149], s[8:9], 0, v[180:181]
	v_pk_mul_f32 v[52:53], v[52:53], v[152:153]
	s_and_b64 vcc, exec, s[4:5]
	v_lshl_add_u64 v[148:149], v[172:173], 1, v[148:149]
	s_cbranch_vccnz .LBB0_536
	v_cvt_pk_bf16_f32 v150, v52, v53
	v_cvt_pk_bf16_f32 v151, v54, v55
	v_cvt_pk_bf16_f32 v152, v48, v49
	v_cvt_pk_bf16_f32 v153, v50, v51
	global_store_dwordx4 v[148:149], v[150:153], off
.LBB0_536:
	s_waitcnt vmcnt(4)
	s_nop 0
	v_lshlrev_b32_e32 v150, 16, v212
	v_and_b32_e32 v151, 0xffff0000, v212
	v_lshlrev_b32_e32 v144, 16, v213
	v_and_b32_e32 v145, 0xffff0000, v213
	v_pk_mul_f32 v[22:23], v[22:23], v[144:145]
	v_lshlrev_b32_e32 v144, 16, v214
	v_and_b32_e32 v145, 0xffff0000, v214
	v_pk_mul_f32 v[16:17], v[16:17], v[144:145]
	v_lshlrev_b32_e32 v144, 16, v215
	v_and_b32_e32 v145, 0xffff0000, v215
	v_pk_mul_f32 v[20:21], v[20:21], v[150:151]
	s_and_b64 vcc, exec, s[4:5]
	v_pk_mul_f32 v[18:19], v[18:19], v[144:145]
	s_cbranch_vccnz .LBB0_538
	v_cvt_pk_bf16_f32 v144, v20, v21
	v_cvt_pk_bf16_f32 v145, v22, v23
	v_cvt_pk_bf16_f32 v146, v16, v17
	v_cvt_pk_bf16_f32 v147, v18, v19
	global_store_dwordx4 v[148:149], v[144:147], off offset:256
.LBB0_538:
	s_waitcnt vmcnt(3)
	s_nop 0
	v_lshlrev_b32_e32 v144, 16, v216
	v_and_b32_e32 v145, 0xffff0000, v216
	v_lshlrev_b32_e32 v140, 16, v217
	v_and_b32_e32 v141, 0xffff0000, v217
	v_pk_mul_f32 v[46:47], v[46:47], v[140:141]
	v_lshlrev_b32_e32 v140, 16, v218
	v_and_b32_e32 v141, 0xffff0000, v218
	v_pk_mul_f32 v[40:41], v[40:41], v[140:141]
	v_lshlrev_b32_e32 v140, 16, v219
	v_and_b32_e32 v141, 0xffff0000, v219
	v_pk_mul_f32 v[42:43], v[42:43], v[140:141]
	v_lshl_add_u64 v[140:141], s[8:9], 0, v[178:179]
	v_pk_mul_f32 v[44:45], v[44:45], v[144:145]
	s_and_b64 vcc, exec, s[4:5]
	v_lshl_add_u64 v[140:141], v[172:173], 1, v[140:141]
	s_cbranch_vccnz .LBB0_540
	v_cvt_pk_bf16_f32 v142, v44, v45
	v_cvt_pk_bf16_f32 v143, v46, v47
	v_cvt_pk_bf16_f32 v144, v40, v41
	v_cvt_pk_bf16_f32 v145, v42, v43
	global_store_dwordx4 v[140:141], v[142:145], off
.LBB0_540:
	s_waitcnt vmcnt(2)
	s_nop 0
	v_lshlrev_b32_e32 v142, 16, v220
	v_and_b32_e32 v143, 0xffff0000, v220
	v_lshlrev_b32_e32 v136, 16, v221
	v_and_b32_e32 v137, 0xffff0000, v221
	v_pk_mul_f32 v[14:15], v[14:15], v[136:137]
	v_lshlrev_b32_e32 v136, 16, v222
	v_and_b32_e32 v137, 0xffff0000, v222
	v_pk_mul_f32 v[8:9], v[8:9], v[136:137]
	v_lshlrev_b32_e32 v136, 16, v223
	v_and_b32_e32 v137, 0xffff0000, v223
	v_pk_mul_f32 v[12:13], v[12:13], v[142:143]
	s_and_b64 vcc, exec, s[4:5]
	v_pk_mul_f32 v[10:11], v[10:11], v[136:137]
	s_cbranch_vccnz .LBB0_542
	v_cvt_pk_bf16_f32 v136, v12, v13
	v_cvt_pk_bf16_f32 v137, v14, v15
	v_cvt_pk_bf16_f32 v138, v8, v9
	v_cvt_pk_bf16_f32 v139, v10, v11
	global_store_dwordx4 v[140:141], v[136:139], off offset:256
.LBB0_542:
	s_waitcnt vmcnt(1)
	s_nop 0
	v_lshlrev_b32_e32 v136, 16, v224
	v_and_b32_e32 v137, 0xffff0000, v224
	v_lshlrev_b32_e32 v132, 16, v225
	v_and_b32_e32 v133, 0xffff0000, v225
	v_pk_mul_f32 v[38:39], v[38:39], v[132:133]
	v_lshlrev_b32_e32 v132, 16, v226
	v_and_b32_e32 v133, 0xffff0000, v226
	v_pk_mul_f32 v[32:33], v[32:33], v[132:133]
	v_lshlrev_b32_e32 v132, 16, v227
	v_and_b32_e32 v133, 0xffff0000, v227
	v_pk_mul_f32 v[34:35], v[34:35], v[132:133]
	v_lshl_add_u64 v[132:133], s[8:9], 0, v[176:177]
	v_pk_mul_f32 v[36:37], v[36:37], v[136:137]
	s_and_b64 vcc, exec, s[4:5]
	v_lshl_add_u64 v[132:133], v[172:173], 1, v[132:133]
	s_cbranch_vccnz .LBB0_544
	v_cvt_pk_bf16_f32 v134, v36, v37
	v_cvt_pk_bf16_f32 v135, v38, v39
	v_cvt_pk_bf16_f32 v136, v32, v33
	v_cvt_pk_bf16_f32 v137, v34, v35
	global_store_dwordx4 v[132:133], v[134:137], off
.LBB0_544:
	s_waitcnt vmcnt(0)
	s_nop 0
	v_lshlrev_b32_e32 v134, 16, v228
	v_and_b32_e32 v135, 0xffff0000, v228
	v_lshlrev_b32_e32 v128, 16, v229
	v_and_b32_e32 v129, 0xffff0000, v229
	v_pk_mul_f32 v[6:7], v[6:7], v[128:129]
	v_lshlrev_b32_e32 v128, 16, v230
	v_and_b32_e32 v129, 0xffff0000, v230
	v_pk_mul_f32 v[0:1], v[0:1], v[128:129]
	v_lshlrev_b32_e32 v128, 16, v231
	v_and_b32_e32 v129, 0xffff0000, v231
	v_pk_mul_f32 v[4:5], v[4:5], v[134:135]
	s_and_b64 vcc, exec, s[4:5]
	v_pk_mul_f32 v[2:3], v[2:3], v[128:129]
	s_cbranch_vccnz .LBB0_546
	v_cvt_pk_bf16_f32 v128, v4, v5
	v_cvt_pk_bf16_f32 v129, v6, v7
	v_cvt_pk_bf16_f32 v130, v0, v1
	v_cvt_pk_bf16_f32 v131, v2, v3
	global_store_dwordx4 v[132:133], v[128:131], off offset:256
